# adds (on the q/k LDS-DMA version, without the v LDS staging): GLA scan v rows loaded with 4 dwordx4 per thread (8 columns x 4 rows) and transposed with v_perm + 8 ds_write_b64, replacing 16 dword load
# speedup vs baseline: 1.0050x; 1.0050x over previous
; __device__ __forceinline__ void gla_scan_phase2(LAS unsigned char* lds, const bf16_t* proj, const float* gbuf, const float* wgu  , const float* bg  ,
;                                                 bf16_t* ob0, bf16_t* ob1) {
;     ...
;         if (wave < 4) {
;             const int d = tid & 127, seg = (tid >> 7) & 1;
;             const int zd = wave;
;             bf16x8 wbh, wbl;
;             {
;                 unsigned hi_[4], lo_[4];
; #pragma unroll
;                 for (int q = 0; q < 4; ++q) {
;                     const float w0 = wgu[(size_t)(dir * 16 + 8 * hh + 2 * q) * 512 + h * 128 + 32 * zd + r], w1 = wgu[(size_t)(dir * 16 + 8 * hh + 2 * q + 1) * 512 + h * 128 + 32 * zd + r];
;                     hi_[q] = pk2(w0, w1); lo_[q] = pk2(w0 - bflo(hi_[q]), w1 - bfhi(hi_[q]));
;                 }
;                 wbh = __builtin_bit_cast(bf16x8, (u32x4){hi_[0], hi_[1], hi_[2], hi_[3]}); wbl = __builtin_bit_cast(bf16x8, (u32x4){lo_[0], lo_[1], lo_[2], lo_[3]});
;             }
;             const float zbias = bg[dir * 512 + h * 128 + 32 * zd + r];
;             const __amdgpu_buffer_rsrc_t prs = __builtin_amdgcn_make_buffer_rsrc((void*)proj, 0, (unsigned)((size_t)MTOK * GINP * 2), 0x00020000);
;             const unsigned qvoff = (unsigned)((16 * seg * GINP + h * 128 + d) * 2), vvoff = (unsigned)((16 * seg * GINP + 1024 + h * 256 + 2 * d) * 2);
;             f32x4 gna, gnb;
;             { const float* grow = gbuf + (size_t)(b * SEQ + (dir ? NCH - 1 : 0) * CH + r) * 32 + dir * 16 + 8 * hh; gna = *(const f32x4*)grow; gnb = *(const f32x4*)(grow + 4); }
;             for (int n = 0; n <= NCH; ++n) {
;                 if (n < NCH) {
;                     const int tok0 = b * SEQ + (dir ? NCH - 1 - n : n) * CH;
;                     LAS unsigned char* set = lds + (n & 1) * G2_SET;
;                     const f32x4 ga = gna, gb = gnb;
;                     const unsigned srow = (unsigned)tok0 * (unsigned)(GINP * 2);
;                     unsigned short qv[16], kv[16];
; #pragma unroll
;                     for (int ii = 0; ii < 16; ++ii) { qv[ii] = __builtin_amdgcn_raw_buffer_load_b16(prs, qvoff, srow + (unsigned)(ii * GINP * 2), 0);
;                                                        kv[ii] = __builtin_amdgcn_raw_buffer_load_b16(prs, qvoff + 1024u, srow + (unsigned)(ii * GINP * 2), 0); }
;                     unsigned vw[16];
; #pragma unroll
.LBB0_217:
	s_and_b64 vcc, exec, s[6:7]
	s_cbranch_vccz .LBB0_212
	s_nop 7
	v_lshl_or_b32 v0, s8, 13, v198
	s_lshl_b32 s0, s15, 7
	v_or_b32_e32 v0, s0, v0
	v_lshlrev_b32_e32 v160, 2, v0
	v_lshl_add_u64 v[0:1], s[16:17], 0, v[160:161]
	v_lshl_add_u64 v[0:1], s[22:23], 2, v[0:1]
	v_mov_b32_e32 v193, v161
	v_lshl_add_u64 v[0:1], v[0:1], 0, v[192:193]
	global_load_dword v2, v[0:1], off
	global_load_dword v3, v[0:1], off offset:2048
	s_movk_i32 s6, 0x1000
	s_lshl_b32 s9, s9, 11
	v_lshlrev_b32_e32 v160, 2, v188
	s_mov_b32 s20, 0
	v_or_b32_e32 v52, s9, v186
	s_waitcnt vmcnt(0)
	v_cvt_pk_bf16_f32 v32, v2, v3
	v_lshlrev_b32_e32 v4, 16, v32
	v_and_b32_e32 v5, 0xffff0000, v32
	v_pk_add_f32 v[2:3], v[2:3], v[4:5] neg_lo:[0,1] neg_hi:[0,1]
	s_nop 0
	v_cvt_pk_bf16_f32 v36, v2, v3
	v_add_co_u32_e32 v2, vcc, s6, v0
	s_movk_i32 s6, 0x2000
	s_nop 0
	v_addc_co_u32_e32 v3, vcc, 0, v1, vcc
	v_add_co_u32_e32 v4, vcc, s6, v0
	s_movk_i32 s6, 0x3000
	s_nop 0
	v_addc_co_u32_e32 v5, vcc, 0, v1, vcc
	global_load_dword v6, v[4:5], off offset:-4096
	global_load_dword v7, v[2:3], off offset:2048
	v_add_co_u32_e32 v0, vcc, s6, v0
	s_lshl_b32 s6, s8, 9
	s_nop 0
	v_addc_co_u32_e32 v1, vcc, 0, v1, vcc
	s_or_b32 s6, s0, s6
	s_cmp_lg_u32 s8, 0
	s_cselect_b64 s[68:69], -1, 0
	s_cmp_eq_u32 s8, 0
	s_cselect_b64 s[48:49], -1, 0
	s_waitcnt vmcnt(0)
	v_cvt_pk_bf16_f32 v33, v6, v7
	v_lshlrev_b32_e32 v2, 16, v33
	v_and_b32_e32 v3, 0xffff0000, v33
	v_pk_add_f32 v[2:3], v[6:7], v[2:3] neg_lo:[0,1] neg_hi:[0,1]
	s_nop 0
	v_cvt_pk_bf16_f32 v37, v2, v3
	global_load_dword v2, v[4:5], off
	global_load_dword v3, v[4:5], off offset:2048
	s_waitcnt vmcnt(0)
	v_cvt_pk_bf16_f32 v34, v2, v3
	v_lshlrev_b32_e32 v4, 16, v34
	v_and_b32_e32 v5, 0xffff0000, v34
	v_pk_add_f32 v[2:3], v[2:3], v[4:5] neg_lo:[0,1] neg_hi:[0,1]
	s_nop 0
	v_cvt_pk_bf16_f32 v38, v2, v3
	global_load_dword v2, v[0:1], off
	global_load_dword v3, v[0:1], off offset:2048
	s_waitcnt vmcnt(0)
	v_cvt_pk_bf16_f32 v35, v2, v3
	v_lshlrev_b32_e32 v0, 16, v35
	v_and_b32_e32 v1, 0xffff0000, v35
	v_pk_add_f32 v[0:1], v[2:3], v[0:1] neg_lo:[0,1] neg_hi:[0,1]
	s_nop 0
	v_cvt_pk_bf16_f32 v39, v0, v1
	v_add_u32_e32 v0, s6, v199
	v_ashrrev_i32_e32 v1, 31, v0
	v_lshl_add_u64 v[0:1], v[0:1], 2, s[18:19]
	global_load_dword v0, v[0:1], off
	v_or_b32_e32 v1, s0, v200
	s_and_b64 s[6:7], s[48:49], exec
	v_lshlrev_b32_e32 v50, 1, v1
	v_lshl_or_b32 v1, s15, 9, v213
	s_cselect_b32 s0, 0, 0x7e0
	v_or_b32_e32 v51, 0x800, v1
	v_or_b32_e32 v1, s0, v186
	v_or_b32_e32 v2, s9, v1
	v_ashrrev_i32_e32 v3, 31, v2
	v_readlane_b32 s6, v253, 19
	v_lshlrev_b64 v[2:3], 7, v[2:3]
	v_readlane_b32 s7, v253, 20
	s_lshl_b32 s28, s8, 6
	v_lshl_add_u64 v[48:49], v[190:191], 0, s[28:29]
	v_lshl_add_u64 v[2:3], s[6:7], 0, v[2:3]
	v_lshl_add_u64 v[2:3], v[2:3], 0, s[28:29]
	v_lshl_add_u64 v[2:3], v[2:3], 0, v[160:161]
	global_load_dwordx4 v[40:43], v[2:3], off offset:16
	global_load_dwordx4 v[44:47], v[2:3], off
	v_or_b32_e32 v53, 0x400, v50
	s_xor_b64 s[50:51], s[40:41], s[48:49]
	s_xor_b64 s[52:53], s[42:43], s[48:49]
	s_xor_b64 s[54:55], s[44:45], s[48:49]
	s_xor_b64 s[56:57], s[46:47], s[48:49]
	s_mov_b32 s8, 63
	s_waitcnt vmcnt(2)
	v_mov_b32_e32 v1, v0
	v_mov_b32_e32 v2, v0
	v_mov_b32_e32 v3, v0
	v_mov_b32_e32 v4, v0
	v_mov_b32_e32 v5, v0
	v_mov_b32_e32 v6, v0
	v_mov_b32_e32 v7, v0
	v_mov_b32_e32 v8, v0
	v_mov_b32_e32 v9, v0
	v_mov_b32_e32 v10, v0
	v_mov_b32_e32 v11, v0
	v_mov_b32_e32 v12, v0
	v_mov_b32_e32 v13, v0
	v_mov_b32_e32 v14, v0
	v_mov_b32_e32 v15, v0
	v_and_b32_e32 v171, 7, v179
	v_lshrrev_b32_e32 v175, 3, v179
	v_mul_u32_u24_e32 v176, 0x6800, v171
	v_lshl_add_u32 v176, v175, 4, v176
	s_lshl_b32 s0, s15, 9
	s_addk_i32 s0, 0x800
	v_add_u32_e32 v176, s0, v176
	v_mul_u32_u24_e32 v177, 0x280, v175
	v_lshl_add_u32 v177, v171, 3, v177
	v_and_b32_e32 v172, 15, v179
	v_lshlrev_b32_e32 v172, 4, v172
	v_bfe_u32 v174, v179, 4, 2
	v_lshrrev_b32_e32 v173, 6, v179
	v_lshl_add_u32 v174, v173, 3, v174
	v_mul_u32_u24_e32 v174, 0x1a00, v174
	v_add_u32_e32 v172, v172, v174
	s_lshl_b32 s0, s15, 8
	v_add_u32_e32 v172, s0, v172
	v_lshlrev_b32_e32 v174, 11, v173
	v_add_u32_e32 v174, 0x1b600, v174
	v_and_b32_e32 v173, 0x7f, v179
	v_lshlrev_b32_e32 v173, 1, v173
	v_bfe_u32 v175, v179, 7, 1
	v_lshl_add_u32 v173, v175, 12, v173
	v_add_u32_e32 v173, 0x1b600, v173
	s_and_b64 s[6:7], s[48:49], exec
	s_cselect_b32 s0, s20, s8
	s_lshl_b32 s0, s0, 5
	s_add_i32 s0, s0, s9
	s_mulk_i32 s0, 0x1a00
	v_readfirstlane_b32 s26, v174
	s_add_u32 s78, s64, s0
	s_addc_u32 s79, s65, 0
	s_add_u32 s80, s78, 0x6800
	s_addc_u32 s81, s79, 0
	s_add_u32 s82, s78, 0x400
	s_addc_u32 s83, s79, 0
	s_add_u32 s24, s80, 0x400
	s_addc_u32 s25, s81, 0
	s_mov_b32 m0, s26
	s_nop 0
	global_load_lds_dwordx4 v172, s[78:79]
	s_add_i32 m0, s26, 0x400
	s_nop 0
	global_load_lds_dwordx4 v172, s[80:81]
	s_add_i32 m0, s26, 0x2000
	s_nop 0
	global_load_lds_dwordx4 v172, s[82:83]
	s_add_i32 m0, s26, 0x2400
	s_nop 0
	global_load_lds_dwordx4 v172, s[24:25]
	s_branch .LBB0_220
.LBB0_219:
	s_or_b64 exec, exec, s[6:7]
	s_mov_b32 s21, 0x5040100
	s_mov_b32 s24, 0x7060302
	v_add_u32_e32 v171, s15, v177
	s_waitcnt vmcnt(2)
	v_perm_b32 v16, v58, v54, s21
	v_perm_b32 v17, v66, v62, s21
	v_perm_b32 v18, v58, v54, s24
	v_perm_b32 v19, v66, v62, s24
	v_perm_b32 v20, v59, v55, s21
	v_perm_b32 v21, v67, v63, s21
	v_perm_b32 v22, v59, v55, s24
	v_perm_b32 v23, v67, v63, s24
	v_perm_b32 v24, v60, v56, s21
	v_perm_b32 v25, v68, v64, s21
	v_perm_b32 v26, v60, v56, s24
	v_perm_b32 v27, v68, v64, s24
	v_perm_b32 v28, v61, v57, s21
	v_perm_b32 v29, v69, v65, s21
	v_perm_b32 v30, v61, v57, s24
	v_perm_b32 v31, v69, v65, s24
	ds_write_b64 v171, v[16:17] offset:18944
	ds_write_b64 v171, v[18:19] offset:19024
	ds_write_b64 v171, v[20:21] offset:19104
	ds_write_b64 v171, v[22:23] offset:19184
	ds_write_b64 v171, v[24:25] offset:19264
	ds_write_b64 v171, v[26:27] offset:19344
	ds_write_b64 v171, v[28:29] offset:19424
	ds_write_b64 v171, v[30:31] offset:19504
	s_waitcnt lgkmcnt(0)
	s_barrier
	s_cmp_eq_u32 s20, 63
	s_cbranch_scc1 .Lg2dma_skip
	s_and_b64 s[6:7], s[48:49], exec
	s_cselect_b32 s0, s20, s8
	s_cselect_b32 s6, 1, -1
	s_add_i32 s0, s0, s6
	s_lshl_b32 s0, s0, 5
	s_add_i32 s0, s0, s9
	s_mulk_i32 s0, 0x1a00
	v_readfirstlane_b32 s26, v174
	s_add_u32 s78, s64, s0
	s_addc_u32 s79, s65, 0
	s_add_u32 s80, s78, 0x6800
	s_addc_u32 s81, s79, 0
	s_add_u32 s82, s78, 0x400
	s_addc_u32 s83, s79, 0
	s_add_u32 s24, s80, 0x400
	s_addc_u32 s25, s81, 0
	s_mov_b32 m0, s26
	s_nop 0
	global_load_lds_dwordx4 v172, s[78:79]
	s_add_i32 m0, s26, 0x400
	s_nop 0
	global_load_lds_dwordx4 v172, s[80:81]
	s_add_i32 m0, s26, 0x2000
	s_nop 0
	global_load_lds_dwordx4 v172, s[82:83]
	s_add_i32 m0, s26, 0x2400
	s_nop 0
	global_load_lds_dwordx4 v172, s[24:25]

; __device__ __forceinline__ void gla_scan_phase2(LAS unsigned char* lds, const bf16_t* proj, const float* gbuf, const float* wgu  , const float* bg  ,
;                                                 bf16_t* ob0, bf16_t* ob1) {
;     ...
;                     const f32x4 ga = gna, gb = gnb;
;                     const unsigned srow = (unsigned)tok0 * (unsigned)(GINP * 2);
;                     unsigned short qv[16], kv[16];
; #pragma unroll
;                     for (int ii = 0; ii < 16; ++ii) { qv[ii] = __builtin_amdgcn_raw_buffer_load_b16(prs, qvoff, srow + (unsigned)(ii * GINP * 2), 0);
;                                                        kv[ii] = __builtin_amdgcn_raw_buffer_load_b16(prs, qvoff + 1024u, srow + (unsigned)(ii * GINP * 2), 0); }
;                     unsigned vw[16];
; #pragma unroll
;                     for (int ii = 0; ii < 16; ++ii) vw[ii] = __builtin_amdgcn_raw_buffer_load_b32(prs, vvoff, srow + (unsigned)(ii * GINP * 2), 0);
;                     { const int n1 = n + 1 < NCH ? n + 1 : n; const float* grow = gbuf + (size_t)(b * SEQ + (dir ? NCH - 1 - n1 : n1) * CH + r) * 32 + dir * 16 + 8 * hh;
;                       gna = *(const f32x4*)grow; gnb = *(const f32x4*)(grow + 4); }
.LBB0_220:
	s_waitcnt vmcnt(4)
	v_cvt_pk_bf16_f32 v102, v44, v45
	v_lshlrev_b32_e32 v16, 16, v102
	v_and_b32_e32 v17, 0xffff0000, v102
	v_cvt_pk_bf16_f32 v103, v46, v47
	v_cvt_pk_bf16_f32 v104, v40, v41
	v_cvt_pk_bf16_f32 v105, v42, v43
	v_pk_add_f32 v[16:17], v[44:45], v[16:17] neg_lo:[0,1] neg_hi:[0,1]
	s_and_b64 s[6:7], s[48:49], exec
	v_cvt_pk_bf16_f32 v44, v16, v17
	v_lshlrev_b32_e32 v16, 16, v103
	v_and_b32_e32 v17, 0xffff0000, v103
	v_pk_add_f32 v[16:17], v[46:47], v[16:17] neg_lo:[0,1] neg_hi:[0,1]
	s_cselect_b32 s0, s20, s8
	v_cvt_pk_bf16_f32 v45, v16, v17
	v_lshlrev_b32_e32 v16, 16, v104
	v_and_b32_e32 v17, 0xffff0000, v104
	v_pk_add_f32 v[16:17], v[40:41], v[16:17] neg_lo:[0,1] neg_hi:[0,1]
	v_lshlrev_b32_e32 v40, 16, v105
	v_cvt_pk_bf16_f32 v46, v16, v17
	v_mfma_f32_32x32x16_bf16 v[16:31], v[102:105], v[32:35], v[0:15]
	v_and_b32_e32 v41, 0xffff0000, v105
	v_add_f32_e64 v40, v42, -v40
	v_add_f32_e64 v41, v43, -v41
	s_lshl_b32 s0, s0, 5
	v_cvt_pk_bf16_f32 v47, v40, v41
	s_add_i32 s0, s0, s9
	s_mulk_i32 s0, 0x1a00
	s_or_b32 s6, s0, 0x1a00
	v_mfma_f32_32x32x16_bf16 v[16:31], v[44:47], v[32:35], v[16:31]
	s_or_b32 s7, s0, 0x3400
	s_add_i32 s15, s0, 0x4e00
	s_add_i32 s21, s0, 0x6800
	s_add_i32 s24, s0, 0x8200
	s_add_i32 s25, s0, 0x9c00
	s_add_i32 s26, s0, 0xb600
	s_add_i32 s28, s0, 0xd000
	s_add_i32 s33, s0, 0xea00
	s_add_i32 s78, s0, 0x10400
	s_add_i32 s79, s0, 0x11e00
	s_add_i32 s80, s0, 0x13800
	s_add_i32 s81, s0, 0x15200
	s_add_i32 s82, s0, 0x16c00
	s_add_i32 s83, s0, 0x18600
	s_cmp_lt_u32 s20, 63
	buffer_load_dwordx4 v[54:57], v176, s[64:67], s0 offen
	buffer_load_dwordx4 v[58:61], v176, s[64:67], s6 offen
	buffer_load_dwordx4 v[62:65], v176, s[64:67], s7 offen
	buffer_load_dwordx4 v[66:69], v176, s[64:67], s15 offen
	s_cselect_b64 s[6:7], -1, 0
	s_cmp_lg_u64 s[6:7], 0
	s_addc_u32 s0, s20, 0
	s_cmp_lg_u64 s[6:7], 0
	s_subb_u32 s6, 0, 0
	v_mfma_f32_32x32x16_bf16 v[16:31], v[102:105], v[36:39], v[16:31]
	s_add_i32 s15, s8, s6
	s_and_b64 s[6:7], s[48:49], exec
	s_cselect_b32 s0, s0, s15
	v_lshl_add_u32 v40, s0, 5, v52
	v_ashrrev_i32_e32 v41, 31, v40
	v_lshlrev_b64 v[40:41], 7, v[40:41]
	v_lshl_add_u64 v[44:45], v[48:49], 0, v[40:41]
	global_load_dwordx4 v[40:43], v[44:45], off offset:16
	s_nop 0
	global_load_dwordx4 v[44:47], v[44:45], off
	s_nop 1
	ds_write_b32 v214, v16
	ds_write_b32 v215, v17
	ds_write_b32 v216, v18
	ds_write_b32 v217, v19
	ds_write_b32 v218, v20
	ds_write_b32 v219, v21
	ds_write_b32 v220, v22
	ds_write_b32 v221, v23
	ds_write_b32 v222, v24
	ds_write_b32 v223, v25
	ds_write_b32 v224, v26
	ds_write_b32 v225, v27
	ds_write_b32 v226, v28
	ds_write_b32 v227, v29
	ds_write_b32 v228, v30
	ds_write_b32 v229, v31
	s_waitcnt lgkmcnt(0)
	s_barrier
; #define LAS __attribute__((address_space(3)))
; __device__ __forceinline__ void gla_scan_phase2(LAS unsigned char* lds, const bf16_t* proj, const float* gbuf, const float* wgu  , const float* bg  ,
;                                                 bf16_t* ob0, bf16_t* ob1) {
;     ...
;                     float cs[16];
; #pragma unroll
;                     for (int ii = 0; ii < 16; ++ii) {
;                         const float z = *(const LAS float*)(lds + G2_Z + ((16 * seg + ii) * 128 + d) * 4);
;                         cs[ii] = fminf(z, 0.f) * (1.4426950408889634f / 16.f) - __builtin_amdgcn_logf(1.f + __builtin_amdgcn_exp2f(fabsf(z) * -1.4426950408889634f)) * (1.f / 16.f);
;                     }
;                     if (dir == 0) {
; #pragma unroll
;                         for (int ii = 1; ii < 16; ++ii) cs[ii] += cs[ii - 1];
;                         *(LAS float*)(lds + G2_SEG + (seg * 128 + d) * 4) = cs[15];
;                     } else {
; #pragma unroll
;     ...
;                         *(LAS float*)(lds + G2_SEG + (seg * 128 + d) * 4) = cs[0];
	ds_read2st64_b32 v[118:119], v230 offset1:2
	ds_read2st64_b32 v[120:121], v230 offset0:4 offset1:6
	ds_read2st64_b32 v[122:123], v230 offset0:8 offset1:10
	ds_read2st64_b32 v[124:125], v230 offset0:12 offset1:14
	ds_read2st64_b32 v[126:127], v230 offset0:16 offset1:18
	ds_read2st64_b32 v[128:129], v230 offset0:20 offset1:22
	ds_read2st64_b32 v[130:131], v230 offset0:24 offset1:26
	ds_read2st64_b32 v[132:133], v230 offset0:28 offset1:30
	s_andn2_b64 vcc, exec, s[68:69]
	s_mov_b64 s[6:7], -1
	s_waitcnt lgkmcnt(4)
	v_mul_f32_e64 v134, |v118|, s1
	v_mul_f32_e64 v135, |v119|, s1
	v_mul_f32_e64 v136, |v120|, s1
	v_mul_f32_e64 v137, |v121|, s1
	v_mul_f32_e64 v138, |v122|, s1
	v_mul_f32_e64 v139, |v123|, s1
	v_mul_f32_e64 v140, |v124|, s1
	v_mul_f32_e64 v141, |v125|, s1
	s_waitcnt lgkmcnt(0)
	v_mul_f32_e64 v142, |v126|, s1
	v_mul_f32_e64 v143, |v127|, s1
	v_mul_f32_e64 v144, |v128|, s1
	v_mul_f32_e64 v145, |v129|, s1
	v_mul_f32_e64 v146, |v130|, s1
	v_mul_f32_e64 v147, |v131|, s1
	v_mul_f32_e64 v148, |v132|, s1
	v_mul_f32_e64 v149, |v133|, s1
	v_exp_f32_e32 v134, v134
	v_exp_f32_e32 v135, v135
	v_exp_f32_e32 v136, v136
	v_exp_f32_e32 v137, v137
	v_exp_f32_e32 v138, v138
	v_exp_f32_e32 v139, v139
	v_exp_f32_e32 v140, v140
	v_exp_f32_e32 v141, v141
	v_exp_f32_e32 v142, v142
	v_exp_f32_e32 v143, v143
	v_exp_f32_e32 v144, v144
	v_exp_f32_e32 v145, v145
	v_exp_f32_e32 v146, v146
	v_exp_f32_e32 v147, v147
	v_exp_f32_e32 v148, v148
	v_exp_f32_e32 v149, v149
	v_min_f32_e32 v118, 0, v118
	v_min_f32_e32 v119, 0, v119
	v_min_f32_e32 v120, 0, v120
	v_min_f32_e32 v121, 0, v121
	v_min_f32_e32 v122, 0, v122
	v_min_f32_e32 v123, 0, v123
	v_min_f32_e32 v124, 0, v124
	v_min_f32_e32 v125, 0, v125
	v_min_f32_e32 v126, 0, v126
	v_min_f32_e32 v127, 0, v127
	v_min_f32_e32 v128, 0, v128
	v_min_f32_e32 v129, 0, v129
	v_min_f32_e32 v130, 0, v130
	v_min_f32_e32 v131, 0, v131
	v_min_f32_e32 v132, 0, v132
	v_min_f32_e32 v133, 0, v133
	v_add_f32_e32 v134, 1.0, v134
	v_add_f32_e32 v135, 1.0, v135
	v_add_f32_e32 v136, 1.0, v136
	v_add_f32_e32 v137, 1.0, v137
	v_add_f32_e32 v138, 1.0, v138
	v_add_f32_e32 v139, 1.0, v139
	v_add_f32_e32 v140, 1.0, v140
	v_add_f32_e32 v141, 1.0, v141
	v_add_f32_e32 v142, 1.0, v142
	v_add_f32_e32 v143, 1.0, v143
	v_add_f32_e32 v144, 1.0, v144
	v_add_f32_e32 v145, 1.0, v145
	v_add_f32_e32 v146, 1.0, v146
	v_add_f32_e32 v147, 1.0, v147
	v_add_f32_e32 v148, 1.0, v148
	v_add_f32_e32 v149, 1.0, v149
	v_log_f32_e32 v134, v134
	v_log_f32_e32 v135, v135
	v_log_f32_e32 v136, v136
	v_log_f32_e32 v137, v137
	v_log_f32_e32 v138, v138
	v_log_f32_e32 v139, v139
	v_log_f32_e32 v140, v140
	v_log_f32_e32 v141, v141
	v_log_f32_e32 v142, v142
	v_log_f32_e32 v143, v143
	v_log_f32_e32 v144, v144
	v_log_f32_e32 v145, v145
	v_log_f32_e32 v146, v146
	v_log_f32_e32 v147, v147
	v_log_f32_e32 v148, v148
	v_log_f32_e32 v149, v149
	v_mul_f32_e32 v134, 0x3d800000, v134
	v_mul_f32_e32 v135, 0x3d800000, v135
	v_mul_f32_e32 v136, 0x3d800000, v136
	v_mul_f32_e32 v137, 0x3d800000, v137
	v_mul_f32_e32 v138, 0x3d800000, v138
	v_mul_f32_e32 v139, 0x3d800000, v139
	v_mul_f32_e32 v140, 0x3d800000, v140
	v_mul_f32_e32 v141, 0x3d800000, v141
	v_mul_f32_e32 v142, 0x3d800000, v142
	v_mul_f32_e32 v143, 0x3d800000, v143
	v_mul_f32_e32 v144, 0x3d800000, v144
	v_mul_f32_e32 v145, 0x3d800000, v145
	v_mul_f32_e32 v146, 0x3d800000, v146
	v_mul_f32_e32 v147, 0x3d800000, v147
	v_mul_f32_e32 v148, 0x3d800000, v148
	v_mul_f32_e32 v149, 0x3d800000, v149
	v_fma_f32 v16, v118, s10, -v134
	v_fma_f32 v25, v119, s10, -v135
	v_fma_f32 v26, v120, s10, -v136
	v_fma_f32 v29, v121, s10, -v137
	v_fma_f32 v30, v122, s10, -v138
	v_fma_f32 v102, v123, s10, -v139
	v_fma_f32 v104, v124, s10, -v140
	v_fma_f32 v105, v125, s10, -v141
	v_fma_f32 v108, v126, s10, -v142
	v_fma_f32 v109, v127, s10, -v143
	v_fma_f32 v111, v128, s10, -v144
	v_fma_f32 v112, v129, s10, -v145
	v_fma_f32 v113, v130, s10, -v146
	v_fma_f32 v114, v131, s10, -v147
	v_fma_f32 v116, v132, s10, -v148
	v_fma_f32 v17, v133, s10, -v149
	s_cbranch_vccnz .LBB0_222
	v_add_f32_e32 v18, v116, v17
	v_add_f32_e32 v19, v114, v18
	v_add_f32_e32 v20, v113, v19
	v_add_f32_e32 v21, v112, v20
	v_add_f32_e32 v22, v111, v21
	v_add_f32_e32 v23, v109, v22
	v_add_f32_e32 v24, v108, v23
	v_add_f32_e32 v27, v105, v24
	v_add_f32_e32 v28, v104, v27
	v_add_f32_e32 v31, v102, v28
	v_add_f32_e32 v103, v30, v31
	v_add_f32_e32 v106, v29, v103
	v_add_f32_e32 v107, v26, v106
	v_add_f32_e32 v110, v25, v107
	v_add_f32_e32 v115, v16, v110
	s_mov_b64 s[6:7], 0

; #define LAS __attribute__((address_space(3)))
; __device__ __forceinline__ float bf2f(unsigned u16) { return __uint_as_float(u16 << 16); }
; #define G2_BAR() do { asm volatile("s_waitcnt lgkmcnt(0)" ::: "memory"); __builtin_amdgcn_s_barrier(); asm volatile("" ::: "memory"); } while (0)
; __device__ __forceinline__ void gla_scan_phase2(LAS unsigned char* lds, const bf16_t* proj, const float* gbuf, const float* wgu  , const float* bg  ,
;                                                 bf16_t* ob0, bf16_t* ob1) {
;     ...
;                     G2_BAR();
;                     {
;                         const float t0 = *(const LAS float*)(lds + G2_SEG + d * 4), t1 = *(const LAS float*)(lds + G2_SEG + (128 + d) * 4);
;                         const float prefix = dir == 0 ? (seg ? t0 : 0.f) : (seg ? 0.f : t1);
;                         const float ebl = __builtin_amdgcn_exp2f(t0 + t1);
;                         unsigned kd[8];
; #pragma unroll
;                         for (int ii = 0; ii < 16; ii += 2) {
;                             const float e0 = __builtin_amdgcn_exp2f(prefix + cs[ii]), e1 = __builtin_amdgcn_exp2f(prefix + cs[ii + 1]);
;                             const float q0 = bf2f(qv[ii]), q1 = bf2f(qv[ii + 1]);
;                             const float k0 = bf2f(kv[ii]) * __builtin_amdgcn_rcpf(e0), k1 = bf2f(kv[ii + 1]) * __builtin_amdgcn_rcpf(e1);
.LBB0_225:
	s_waitcnt vmcnt(6)
	ds_write_b32 v231, v115
	s_waitcnt lgkmcnt(0)
	s_barrier
	v_add_u32_e32 v25, s11, v202
	ds_read2st64_b32 v[104:105], v25 offset1:2
	ds_read_u16 v98, v173
	ds_read_u16 v100, v173 offset:256
	ds_read_u16 v94, v173 offset:512
	ds_read_u16 v96, v173 offset:768
	ds_read_u16 v90, v173 offset:1024
	ds_read_u16 v92, v173 offset:1280
	ds_read_u16 v82, v173 offset:1536
	ds_read_u16 v84, v173 offset:1792
	ds_read_u16 v99, v173 offset:8192
	ds_read_u16 v101, v173 offset:8448
	ds_read_u16 v95, v173 offset:8704
	ds_read_u16 v97, v173 offset:8960
	ds_read_u16 v91, v173 offset:9216
	ds_read_u16 v93, v173 offset:9472
	ds_read_u16 v83, v173 offset:9728
	ds_read_u16 v85, v173 offset:9984
	ds_read_u16 v86, v173 offset:2048
	ds_read_u16 v88, v173 offset:2304
	ds_read_u16 v78, v173 offset:2560
	ds_read_u16 v80, v173 offset:2816
	ds_read_u16 v74, v173 offset:3072
	ds_read_u16 v76, v173 offset:3328
	ds_read_u16 v70, v173 offset:3584
	ds_read_u16 v72, v173 offset:3840
	ds_read_u16 v87, v173 offset:10240
	ds_read_u16 v89, v173 offset:10496
	ds_read_u16 v79, v173 offset:10752
	ds_read_u16 v81, v173 offset:11008
	ds_read_u16 v75, v173 offset:11264
	ds_read_u16 v77, v173 offset:11520
	ds_read_u16 v71, v173 offset:11776
	ds_read_u16 v73, v173 offset:12032
	s_bitcmp1_b32 s20, 0
	s_cselect_b32 s0, 0xa800, 0
	s_waitcnt lgkmcnt(0)
	v_lshlrev_b32_e32 v111, 16, v100
	s_add_i32 s15, s0, 0
	s_waitcnt lgkmcnt(0)
; #define LAS __attribute__((address_space(3)))
; __device__ __forceinline__ unsigned pk2(float lo, float hi) { f32x2 v = {lo, hi}; bf16x2_t b = __builtin_convertvector(v, bf16x2_t); return __builtin_bit_cast(unsigned, b); }
; __device__ __forceinline__ void gla_scan_phase2(LAS unsigned char* lds, const bf16_t* proj, const float* gbuf, const float* wgu  , const float* bg  ,
;                                                 bf16_t* ob0, bf16_t* ob1) {
;     ...
;                         const float t0 = *(const LAS float*)(lds + G2_SEG + d * 4), t1 = *(const LAS float*)(lds + G2_SEG + (128 + d) * 4);
;                         const float prefix = dir == 0 ? (seg ? t0 : 0.f) : (seg ? 0.f : t1);
;                         const float ebl = __builtin_amdgcn_exp2f(t0 + t1);
;                         unsigned kd[8];
; #pragma unroll
;                         for (int ii = 0; ii < 16; ii += 2) {
;                             const float e0 = __builtin_amdgcn_exp2f(prefix + cs[ii]), e1 = __builtin_amdgcn_exp2f(prefix + cs[ii + 1]);
;                             const float q0 = bf2f(qv[ii]), q1 = bf2f(qv[ii + 1]);
;                             const float k0 = bf2f(kv[ii]) * __builtin_amdgcn_rcpf(e0), k1 = bf2f(kv[ii + 1]) * __builtin_amdgcn_rcpf(e1);
;                             const unsigned qd = pk2(q0 * e0, q1 * e1);
;                             const unsigned ki = pk2(k0, k1);
;                             kd[ii >> 1] = pk2(k0 * ebl, k1 * ebl);
;                             const int i0 = 16 * seg + ii;
;                             *(LAS unsigned short*)(set + G2_QD + i0 * 272 + d * 2) = (unsigned short)(qd & 0xffffu);
;                             *(LAS unsigned short*)(set + G2_QD + (i0 + 1) * 272 + d * 2) = (unsigned short)(qd >> 16);
;                             *(LAS unsigned short*)(lds + G2_KI + i0 * 272 + d * 2) = (unsigned short)(ki & 0xffffu);
;                             *(LAS unsigned short*)(lds + G2_KI + (i0 + 1) * 272 + d * 2) = (unsigned short)(ki >> 16);
;                         }
;                         *(LAS u32x4*)(set + G2_KDT + d * 80 + seg * 32) = (u32x4){kd[0], kd[1], kd[2], kd[3]};
;                         *(LAS u32x4*)(set + G2_KDT + d * 80 + seg * 32 + 16) = (u32x4){kd[4], kd[5], kd[6], kd[7]};
;                         if (seg == 0) *(LAS float*)(set + G2_EBL + d * 4) = ebl;
	v_cndmask_b32_e64 v25, v104, 0, s[38:39]
	v_cndmask_b32_e64 v26, 0, v105, s[38:39]
	v_cndmask_b32_e64 v102, v26, v25, s[48:49]
	v_add_f32_e32 v16, v16, v102
	v_exp_f32_e32 v108, v16
	v_add_f32_e32 v16, v110, v102
	v_exp_f32_e32 v109, v16
	v_add_f32_e32 v16, v104, v105
	v_rcp_f32_e32 v104, v108
	v_lshlrev_b32_e32 v110, 16, v98
	v_rcp_f32_e32 v105, v109
	v_pk_mul_f32 v[108:109], v[108:109], v[110:111]
	s_nop 0
	v_lshlrev_b32_e32 v101, 16, v101
	v_cvt_pk_bf16_f32 v25, v108, v109
	v_add3_u32 v108, s15, v201, v211
	v_lshlrev_b32_e32 v100, 16, v99
	ds_write_b16 v108, v25
	ds_write_b16_d16_hi v108, v25 offset:272
	v_add_f32_e32 v25, v107, v102
	v_pk_mul_f32 v[98:99], v[104:105], v[100:101]
	v_exp_f32_e32 v100, v25
	v_add_f32_e32 v25, v106, v102
	v_exp_f32_e32 v101, v25
	v_lshlrev_b32_e32 v107, 16, v96
	v_lshlrev_b32_e32 v106, 16, v94
	v_rcp_f32_e32 v104, v100
	v_rcp_f32_e32 v105, v101
	v_pk_mul_f32 v[100:101], v[100:101], v[106:107]
	v_cvt_pk_bf16_f32 v26, v98, v99
	v_cvt_pk_bf16_f32 v25, v100, v101
	ds_write_b16 v232, v26
	ds_write_b16_d16_hi v232, v26 offset:272
	ds_write_b16 v108, v25 offset:544
	ds_write_b16_d16_hi v108, v25 offset:816
	v_add_f32_e32 v25, v103, v102
	v_exp_f32_e32 v16, v16
	v_exp_f32_e32 v30, v25
	v_add_f32_e32 v25, v31, v102
	v_exp_f32_e32 v31, v25
	s_nop 0
	v_lshlrev_b32_e32 v97, 16, v97
	v_lshlrev_b32_e32 v96, 16, v95
	v_pk_mul_f32 v[94:95], v[104:105], v[96:97]
	v_pk_mul_f32 v[98:99], v[16:17], v[98:99] op_sel_hi:[0,1]
	v_cvt_pk_bf16_f32 v26, v94, v95
	v_pk_mul_f32 v[94:95], v[16:17], v[94:95] op_sel_hi:[0,1]
	v_lshlrev_b32_e32 v97, 16, v92
	v_lshlrev_b32_e32 v96, 16, v90
	v_cvt_pk_bf16_f32 v98, v98, v99
	v_cvt_pk_bf16_f32 v99, v94, v95
	v_rcp_f32_e32 v94, v30
	v_rcp_f32_e32 v95, v31
	v_pk_mul_f32 v[30:31], v[30:31], v[96:97]
	ds_write_b16 v232, v26 offset:544
	ds_write_b16_d16_hi v232, v26 offset:816
	v_cvt_pk_bf16_f32 v25, v30, v31
	ds_write_b16 v108, v25 offset:1088
	ds_write_b16_d16_hi v108, v25 offset:1360
	v_add_f32_e32 v25, v28, v102
	v_exp_f32_e32 v26, v25
	v_add_f32_e32 v25, v27, v102
	v_exp_f32_e32 v27, v25
	s_nop 0
	v_lshlrev_b32_e32 v31, 16, v93
	v_lshlrev_b32_e32 v30, 16, v91
	v_pk_mul_f32 v[30:31], v[94:95], v[30:31]
	v_rcp_f32_e32 v28, v26
	v_cvt_pk_bf16_f32 v29, v30, v31
	v_pk_mul_f32 v[30:31], v[16:17], v[30:31] op_sel_hi:[0,1]
	v_cvt_pk_bf16_f32 v100, v30, v31
	ds_write_b16 v232, v29 offset:1088
	ds_write_b16_d16_hi v232, v29 offset:1360
	v_rcp_f32_e32 v29, v27
	v_lshlrev_b32_e32 v31, 16, v84
	v_lshlrev_b32_e32 v30, 16, v82
	v_pk_mul_f32 v[26:27], v[26:27], v[30:31]
	v_add_f32_e32 v24, v24, v102
	v_cvt_pk_bf16_f32 v25, v26, v27
	v_add_f32_e32 v23, v23, v102
	s_nop 0
	v_lshlrev_b32_e32 v27, 16, v85
	v_lshlrev_b32_e32 v26, 16, v83
	ds_write_b16 v108, v25 offset:1632
	ds_write_b16_d16_hi v108, v25 offset:1904
	v_exp_f32_e32 v24, v24
	v_exp_f32_e32 v25, v23
	v_pk_mul_f32 v[26:27], v[28:29], v[26:27]
	s_nop 0
	v_lshlrev_b32_e32 v29, 16, v88
	v_cvt_pk_bf16_f32 v28, v26, v27
	v_pk_mul_f32 v[26:27], v[16:17], v[26:27] op_sel_hi:[0,1]
	ds_write_b16 v232, v28 offset:1632
	ds_write_b16_d16_hi v232, v28 offset:1904
	v_lshlrev_b32_e32 v28, 16, v86
	v_cvt_pk_bf16_f32 v101, v26, v27
	v_rcp_f32_e32 v26, v24
	v_rcp_f32_e32 v27, v25
	v_pk_mul_f32 v[24:25], v[24:25], v[28:29]
	v_add_f32_e32 v22, v22, v102
	v_cvt_pk_bf16_f32 v23, v24, v25
	v_add_f32_e32 v21, v21, v102
	ds_write_b16 v108, v23 offset:2176
	ds_write_b16_d16_hi v108, v23 offset:2448
	v_exp_f32_e32 v22, v22
	v_exp_f32_e32 v23, v21
	s_nop 0
	v_lshlrev_b32_e32 v25, 16, v89
	v_lshlrev_b32_e32 v24, 16, v87
	v_pk_mul_f32 v[24:25], v[26:27], v[24:25]
	v_lshlrev_b32_e32 v29, 16, v80
	v_cvt_pk_bf16_f32 v26, v24, v25
	v_lshlrev_b32_e32 v28, 16, v78
	ds_write_b16 v232, v26 offset:2176
	ds_write_b16_d16_hi v232, v26 offset:2448
	v_rcp_f32_e32 v26, v22
	v_rcp_f32_e32 v27, v23
	v_pk_mul_f32 v[22:23], v[22:23], v[28:29]
	v_add_f32_e32 v20, v20, v102
	v_cvt_pk_bf16_f32 v21, v22, v23
	v_add_f32_e32 v19, v19, v102
	ds_write_b16 v108, v21 offset:2720
	ds_write_b16_d16_hi v108, v21 offset:2992
	v_exp_f32_e32 v20, v20
	v_exp_f32_e32 v21, v19
	s_nop 0
	v_lshlrev_b32_e32 v23, 16, v81
	v_lshlrev_b32_e32 v22, 16, v79
	v_pk_mul_f32 v[22:23], v[26:27], v[22:23]
	v_pk_mul_f32 v[24:25], v[16:17], v[24:25] op_sel_hi:[0,1]
	v_cvt_pk_bf16_f32 v26, v22, v23
	v_pk_mul_f32 v[22:23], v[16:17], v[22:23] op_sel_hi:[0,1]
	v_cvt_pk_bf16_f32 v24, v24, v25
	v_cvt_pk_bf16_f32 v25, v22, v23
	v_rcp_f32_e32 v22, v20
	v_rcp_f32_e32 v23, v21
	ds_write_b16 v232, v26 offset:2720
	ds_write_b16_d16_hi v232, v26 offset:2992
	v_lshlrev_b32_e32 v27, 16, v76
	v_lshlrev_b32_e32 v26, 16, v74
	v_pk_mul_f32 v[20:21], v[20:21], v[26:27]
	v_add_f32_e32 v18, v18, v102
	v_cvt_pk_bf16_f32 v19, v20, v21
	s_nop 0
	v_lshlrev_b32_e32 v21, 16, v77
	v_lshlrev_b32_e32 v20, 16, v75
	v_pk_mul_f32 v[20:21], v[22:23], v[20:21]
	ds_write_b16 v108, v19 offset:3264
	ds_write_b16_d16_hi v108, v19 offset:3536
	v_cvt_pk_bf16_f32 v22, v20, v21
	v_pk_mul_f32 v[20:21], v[16:17], v[20:21] op_sel_hi:[0,1]
	v_add_f32_e32 v17, v17, v102
	v_exp_f32_e32 v18, v18
	v_exp_f32_e32 v19, v17
	v_cvt_pk_bf16_f32 v26, v20, v21
	ds_write_b16 v232, v22 offset:3264
	ds_write_b16_d16_hi v232, v22 offset:3536
	v_rcp_f32_e32 v20, v18
	v_rcp_f32_e32 v21, v19
	v_lshlrev_b32_e32 v23, 16, v72
	v_lshlrev_b32_e32 v22, 16, v70
	v_pk_mul_f32 v[18:19], v[18:19], v[22:23]
	s_nop 0
	v_cvt_pk_bf16_f32 v17, v18, v19
	s_nop 0
	v_lshlrev_b32_e32 v19, 16, v73
	v_lshlrev_b32_e32 v18, 16, v71
	v_pk_mul_f32 v[18:19], v[20:21], v[18:19]
	s_nop 0
	v_cvt_pk_bf16_f32 v20, v18, v19
	v_pk_mul_f32 v[18:19], v[16:17], v[18:19] op_sel_hi:[0,1]
	ds_write_b16 v108, v17 offset:3808
	ds_write_b16_d16_hi v108, v17 offset:4080
	ds_write_b16 v232, v20 offset:3808
	ds_write_b16_d16_hi v232, v20 offset:4080
	v_add3_u32 v17, s15, v203, v204
	v_cvt_pk_bf16_f32 v27, v18, v19
	ds_write_b128 v17, v[98:101] offset:8704
	ds_write_b128 v17, v[24:27] offset:8720
	s_and_saveexec_b64 s[6:7], s[38:39]
	s_cbranch_execz .LBB0_219
	v_add_u32_e32 v17, s15, v202
	ds_write_b32 v17, v16 offset:41984
	s_branch .LBB0_219
